# v24 + fox z-row loads go straight to their final registers, vmcnt(0) moved from before the last tile's compute to the loop exit
# speedup vs baseline: 1.0088x; 1.0029x over previous
; DI void fox_unit(const bf16* PR, const float* AUX, const float* bfp, bf16* MIX, char* sm, int b, int h, int qb, bool do_cs) {
;     ...
;     for (int it_ = -1, nt_ = (4 * qb + 4); it_ < nt_; ++it_) {
;         const bool more_ = it_ + 1 < nt_;
;         if (!more_) {
; #pragma unroll
;             for (int j = 0; j < 4; ++j) zpre[j] = *(const u32x4*)(zrow0 + (size_t)((lane >> 3) + 8 * j) * NP + 8 * (lane & 7));
;         }
.LBB0_342:
	s_add_i32 s36, s33, 1
	s_cmp_lt_u32 s36, s31
	s_cselect_b64 s[20:21], -1, 0
	s_mov_b64 s[22:23], -1
	s_and_b64 vcc, exec, s[20:21]
	s_cbranch_vccnz .LBB0_344
	global_load_dwordx4 v[106:109], v[162:163], off
	global_load_dwordx4 v[102:105], v[164:165], off
	global_load_dwordx4 v[98:101], v[166:167], off
	global_load_dwordx4 v[86:89], v[168:169], off
	s_mov_b64 s[22:23], 0

; DI float bf2f(unsigned h) { return __uint_as_float(h << 16); }
; #define MFMA32(a, b, c) __builtin_amdgcn_mfma_f32_32x32x16_bf16((a), (b), (c), 0, 0, 0)
; DI void qk_tile(const char* kb, const bf16x8 (&qr)[5], int r32, int hi, f32x16& x0, f32x16& x1) {
;     bf16x8 kf[10];
; #pragma unroll
;     for (int d0 = 0; d0 < 4; ++d0) {
;         kf[2 * d0] = *(const bf16x8*)(kb + (2 * d0 + hi) * 1024 + r32 * 16);
;         kf[2 * d0 + 1] = *(const bf16x8*)(kb + (2 * d0 + hi) * 1024 + 512 + r32 * 16);
;     }
;     kf[8] = *(const bf16x8*)(kb + 8192 + r32 * 16);
;     kf[9] = *(const bf16x8*)(kb + 8192 + 512 + r32 * 16);
;     asm volatile("s_waitcnt lgkmcnt(0)" ::: "memory");
; #pragma unroll
;     for (int i = 0; i < 16; ++i) { x0[i] = 0.f; x1[i] = 0.f; }
; #pragma unroll
;     for (int d0 = 0; d0 < 5; ++d0) { x0 = MFMA32(kf[2 * d0], qr[d0], x0); x1 = MFMA32(kf[2 * d0 + 1], qr[d0], x1); }
; }
; DI void fox_unit(const bf16* PR, const float* AUX, const float* bfp, bf16* MIX, char* sm, int b, int h, int qb, bool do_cs) {
;     ...
;         if (it_ >= 0) { const int kt = nt_ - 1 - it_; const char* cb = sm + (it_ & 1) * STG; { if (64 * kt <= wq0 + 31) {
;               bool skip_ = false;
;               if (64 * kt + 63 + 384 < q0) {
;                   unsigned kb_ = 0u;
; #pragma unroll
;                   for (int w = 0; w < 8; ++w) { const unsigned v_ = kmx[(it_ & 1) * 8 + w]; kb_ = v_ > kb_ ? v_ : kb_; }
;                   const float ub = C2 * (q1 * bf2f(kb_) + 8.f * (cref - cbuf[64 * kt + 63]));
;                   skip_ = __all(ub - m < -151.f);
;               }
;               if (!skip_) {
;                   f32x16 x0, x1; qk_tile(cb, qr, r32, hi, x0, x1); bf16x8 vf[8]; v_load(cb + 9216, lane, hi, vf);
;                   if (64 * kt + 63 > wq0) mask_tile(x0, x1, 0, t - 64 * kt, hi);
.LBB0_347:
.LBB0_348:
	s_add_i32 s19, s18, 64
	s_cmp_gt_i32 s19, s34
	s_cbranch_scc1 .LBB0_357
	s_and_b32 s19, s33, 1
	s_add_i32 s22, s18, 0x1ff
	s_cmp_ge_i32 s22, s26
	s_cselect_b64 s[22:23], -1, 0
	s_and_b64 vcc, exec, s[22:23]
	s_cbranch_vccnz .LBB0_351
	s_lshl_b32 s22, s19, 5
	s_add_i32 s22, s22, 0
	s_add_i32 s22, s22, 0x13580
	v_mov_b32_e32 v0, s22
	ds_read_b128 v[34:37], v0
	ds_read_b128 v[38:41], v0 offset:16
	v_mov_b32_e32 v0, s35
	ds_read_b32 v0, v0 offset:508
	s_waitcnt lgkmcnt(0)
	v_max_u32_e32 v34, v35, v34
	v_max3_u32 v34, v37, v36, v34
	v_max3_u32 v34, v39, v38, v34
	v_max3_u32 v34, v41, v40, v34
	v_lshlrev_b32_e32 v149, 16, v34
	v_sub_f32_e32 v160, v195, v0
	v_pk_mul_f32 v[34:35], v[160:161], v[148:149]
	s_nop 0
	v_add_f32_e32 v0, v34, v35
	v_fma_f32 v0, v0, s92, -v237
	v_cmp_gt_f32_e32 vcc, s60, v0
	s_cmp_lg_u64 vcc, exec
	s_cselect_b64 s[22:23], -1, 0
.LBB0_351:
	s_andn2_b64 vcc, exec, s[22:23]
	s_cbranch_vccnz .LBB0_357
	s_mulk_i32 s19, 0x4800
	s_add_i32 s19, s19, 0
	v_add_u32_e32 v0, s19, v197
	v_add_u32_e32 v85, v0, v198
	ds_read_b128 v[34:37], v85
	s_waitcnt vmcnt(4)
	ds_read_b128 v[38:41], v85 offset:512
	ds_read_b128 v[114:117], v85 offset:2048
	ds_read_b128 v[118:121], v85 offset:2560
	s_add_i32 s22, s18, 0x7f
	s_cmp_le_i32 s22, s28
	s_waitcnt lgkmcnt(3)
	v_mfma_f32_32x32x16_bf16 v[50:65], v[34:37], v[66:69], 0
	s_waitcnt lgkmcnt(2)
	v_mfma_f32_32x32x16_bf16 v[34:49], v[38:41], v[66:69], 0
	s_waitcnt lgkmcnt(1)
	v_mfma_f32_32x32x16_bf16 v[50:65], v[114:117], v[70:73], v[50:65]
	s_waitcnt lgkmcnt(0)
	v_mfma_f32_32x32x16_bf16 v[34:49], v[118:121], v[70:73], v[34:49]
	ds_read_b128 v[114:117], v85 offset:4096
	ds_read_b128 v[118:121], v85 offset:4608
	s_waitcnt lgkmcnt(1)
	v_mfma_f32_32x32x16_bf16 v[50:65], v[114:117], v[74:77], v[50:65]
	s_waitcnt lgkmcnt(0)
	v_mfma_f32_32x32x16_bf16 v[34:49], v[118:121], v[74:77], v[34:49]
	ds_read_b128 v[114:117], v85 offset:6144
	ds_read_b128 v[118:121], v85 offset:6656
	s_waitcnt lgkmcnt(1)
	v_mfma_f32_32x32x16_bf16 v[50:65], v[114:117], v[78:81], v[50:65]
	ds_read_b128 v[114:117], v0 offset:8192
	ds_read_b128 v[238:241], v0 offset:8704
	v_add3_u32 v0, s19, v199, v196
	v_add3_u32 v0, v0, v200, v202
	ds_read_b64_tr_b16 v[142:143], v0 offset:9216
	ds_read_b64_tr_b16 v[144:145], v0 offset:9728
	ds_read_b64_tr_b16 v[134:135], v0 offset:10240
	ds_read_b64_tr_b16 v[136:137], v0 offset:10752
	ds_read_b64_tr_b16 v[138:139], v0 offset:13312
	ds_read_b64_tr_b16 v[140:141], v0 offset:13824
	ds_read_b64_tr_b16 v[130:131], v0 offset:14336
	ds_read_b64_tr_b16 v[132:133], v0 offset:14848
	s_waitcnt lgkmcnt(10)
	v_mfma_f32_32x32x16_bf16 v[34:49], v[118:121], v[78:81], v[34:49]
	s_waitcnt lgkmcnt(9)
	v_mfma_f32_32x32x16_bf16 v[50:65], v[114:117], v[110:113], v[50:65]
	ds_read_b64_tr_b16 v[126:127], v0 offset:11264
	ds_read_b64_tr_b16 v[128:129], v0 offset:11776
	ds_read_b64_tr_b16 v[118:119], v0 offset:12288
	ds_read_b64_tr_b16 v[120:121], v0 offset:12800
	ds_read_b64_tr_b16 v[122:123], v0 offset:15360
	ds_read_b64_tr_b16 v[124:125], v0 offset:15872
	ds_read_b64_tr_b16 v[114:115], v0 offset:16384
	ds_read_b64_tr_b16 v[116:117], v0 offset:16896
	s_waitcnt lgkmcnt(14)
	v_mfma_f32_32x32x16_bf16 v[34:49], v[238:241], v[110:113], v[34:49]
	s_cbranch_scc1 .LBB0_354
	v_cmp_le_i32_e32 vcc, v204, v235
	s_nop 9
	v_cndmask_b32_e32 v34, v180, v34, vcc
	v_cmp_lt_i32_e32 vcc, v203, v235
	s_nop 1
	v_cndmask_b32_e32 v51, v180, v51, vcc
	v_cmp_le_i32_e32 vcc, v203, v235
	s_nop 1
	v_cndmask_b32_e32 v50, v180, v50, vcc
	v_cmp_le_i32_e32 vcc, v205, v235
	s_nop 1
	v_cndmask_b32_e32 v35, v180, v35, vcc
	v_cmp_le_i32_e32 vcc, v206, v235
	s_nop 1
	v_cndmask_b32_e32 v52, v180, v52, vcc
	v_cmp_le_i32_e32 vcc, v207, v235
	s_nop 1
	v_cndmask_b32_e32 v36, v180, v36, vcc
	v_cmp_le_i32_e32 vcc, v208, v235
	s_nop 1
	v_cndmask_b32_e32 v53, v180, v53, vcc
	v_cmp_le_i32_e32 vcc, v209, v235
	s_nop 1
	v_cndmask_b32_e32 v37, v180, v37, vcc
	v_cmp_le_i32_e32 vcc, v210, v235
	s_nop 1
	v_cndmask_b32_e32 v54, v180, v54, vcc
	v_cmp_le_i32_e32 vcc, v211, v235
	s_nop 1
	v_cndmask_b32_e32 v38, v180, v38, vcc
	v_cmp_le_i32_e32 vcc, v212, v235
	s_nop 1
	v_cndmask_b32_e32 v55, v180, v55, vcc
	v_cmp_le_i32_e32 vcc, v213, v235
	s_nop 1
	v_cndmask_b32_e32 v39, v180, v39, vcc
	v_cmp_le_i32_e32 vcc, v214, v235
	s_nop 1
	v_cndmask_b32_e32 v56, v180, v56, vcc
	v_cmp_le_i32_e32 vcc, v215, v235
	s_nop 1
	v_cndmask_b32_e32 v40, v180, v40, vcc
	v_cmp_le_i32_e32 vcc, v216, v235
	s_nop 1
	v_cndmask_b32_e32 v57, v180, v57, vcc
	v_cmp_le_i32_e32 vcc, v217, v235
	s_nop 1
	v_cndmask_b32_e32 v41, v180, v41, vcc
	v_cmp_le_i32_e32 vcc, v218, v235
	s_nop 1
	v_cndmask_b32_e32 v58, v180, v58, vcc
	v_cmp_le_i32_e32 vcc, v219, v235
	s_nop 1
	v_cndmask_b32_e32 v42, v180, v42, vcc
	v_cmp_le_i32_e32 vcc, v220, v235
	s_nop 1
	v_cndmask_b32_e32 v59, v180, v59, vcc
	v_cmp_le_i32_e32 vcc, v221, v235
	s_nop 1
	v_cndmask_b32_e32 v43, v180, v43, vcc
	v_cmp_le_i32_e32 vcc, v222, v235
	s_nop 1
	v_cndmask_b32_e32 v60, v180, v60, vcc
	v_cmp_le_i32_e32 vcc, v223, v235
	s_nop 1
	v_cndmask_b32_e32 v44, v180, v44, vcc
	v_cmp_le_i32_e32 vcc, v224, v235
	s_nop 1
	v_cndmask_b32_e32 v61, v180, v61, vcc
	v_cmp_le_i32_e32 vcc, v225, v235
	s_nop 1
	v_cndmask_b32_e32 v45, v180, v45, vcc
	v_cmp_le_i32_e32 vcc, v226, v235
	s_nop 1
	v_cndmask_b32_e32 v62, v180, v62, vcc
	v_cmp_le_i32_e32 vcc, v227, v235
	s_nop 1
	v_cndmask_b32_e32 v46, v180, v46, vcc
	v_cmp_le_i32_e32 vcc, v228, v235
	s_nop 1
	v_cndmask_b32_e32 v63, v180, v63, vcc
	v_cmp_le_i32_e32 vcc, v229, v235
	s_nop 1
	v_cndmask_b32_e32 v47, v180, v47, vcc
	v_cmp_le_i32_e32 vcc, v230, v235
	s_nop 1
	v_cndmask_b32_e32 v64, v180, v64, vcc
	v_cmp_le_i32_e32 vcc, v231, v235
	s_nop 1
	v_cndmask_b32_e32 v48, v180, v48, vcc
	v_cmp_le_i32_e32 vcc, v232, v235
	s_nop 1
	v_cndmask_b32_e32 v65, v180, v65, vcc
	v_cmp_le_i32_e32 vcc, v233, v235
	s_nop 1
	v_cndmask_b32_e32 v49, v180, v49, vcc

; DI float bf2f(unsigned h) { return __uint_as_float(h << 16); }
; DI unsigned cvtpk(float lo, float hi) { f32x2_t v = {lo, hi}; bf16x2_t b = __builtin_convertvector(v, bf16x2_t); return __builtin_bit_cast(unsigned, b); }
; DI float silu_f(float z) { return z * sigm_f(z); }
; DI void write_out_z(const f32x16& o0, const f32x16& o1, float sc, const u32x4 (&zpre)[4], bf16* orow0, size_t opitch, float* st, int lane) {
;     const int q = lane & 31, hi = lane >> 5;
; #pragma unroll
;     for (int d0 = 0; d0 < 2; ++d0)
; #pragma unroll
;         for (int gq = 0; gq < 4; ++gq) {
;             const int ch = 8 * d0 + 2 * gq + hi; const f32x16& o = d0 ? o1 : o0;
;             *(f32x4*)(st + q * 64 + ((ch ^ (q & 15)) << 2)) = (f32x4){o[4 * gq] * sc, o[4 * gq + 1] * sc, o[4 * gq + 2] * sc, o[4 * gq + 3] * sc};
;         }
; #pragma unroll
;     for (int j = 0; j < 4; ++j) {
;         const int row = (lane >> 3) + 8 * j, c = lane & 7;
;         const f32x4 a = *(const f32x4*)(st + row * 64 + (((2 * c) ^ (row & 15)) << 2)), b = *(const f32x4*)(st + row * 64 + (((2 * c + 1) ^ (row & 15)) << 2));
;         const u32x4 zz = zpre[j];
;         u32x4 w;
;         w.x = cvtpk(a[0] * silu_f(bf2f(zz.x & 0xffffu)), a[1] * silu_f(bf2f(zz.x >> 16)));
;         w.y = cvtpk(a[2] * silu_f(bf2f(zz.y & 0xffffu)), a[3] * silu_f(bf2f(zz.y >> 16)));
;         w.z = cvtpk(b[0] * silu_f(bf2f(zz.z & 0xffffu)), b[1] * silu_f(bf2f(zz.z >> 16)));
;         w.w = cvtpk(b[2] * silu_f(bf2f(zz.w & 0xffffu)), b[3] * silu_f(bf2f(zz.w >> 16)));
;         *(u32x4*)(orow0 + (size_t)row * opitch + 8 * c) = w;
;     }
; }
; DI void fox_unit(const bf16* PR, const float* AUX, const float* bfp, bf16* MIX, char* sm, int b, int h, int qb, bool do_cs) {
;     ...
;     const float lt = l + __shfl_xor(l, 32);
;     write_out_z(o0, o1, lt > 0.f ? 1.f / lt : 0.f, zpre, MIX + (rb + wq0) * D + 64 * h, D, (float*)(sm + L_TACC) + wid * 2048, lane);
.LBB0_367:
	s_waitcnt vmcnt(0)
	ds_bpermute_b32 v0, v187, v236
	s_lshl_b64 s[2:3], s[6:7], 11
	s_add_u32 s2, s96, s2
	s_addc_u32 s3, s97, s3
	s_add_u32 s2, s2, s8
	s_waitcnt lgkmcnt(0)
	v_add_f32_e32 v0, v236, v0
	v_div_scale_f32 v34, s[4:5], v0, v0, 1.0
	v_rcp_f32_e32 v35, v34
	v_div_scale_f32 v36, vcc, 1.0, v0, 1.0
	s_addc_u32 s3, s3, s9
	v_fma_f32 v37, -v34, v35, 1.0
	v_fmac_f32_e32 v35, v37, v35
	v_mul_f32_e32 v37, v36, v35
	s_waitcnt vmcnt(4)
	v_fma_f32 v38, -v34, v37, v36
	v_fmac_f32_e32 v37, v38, v35
	v_fma_f32 v34, -v34, v37, v36
	v_div_fmas_f32 v34, v34, v35, v37
	v_div_fixup_f32 v34, v34, v0, 1.0
	v_cmp_lt_f32_e32 vcc, 0, v0
	s_lshl_b32 s4, s27, 13
	s_add_i32 s4, s4, 0
	v_cndmask_b32_e32 v0, 0, v34, vcc
	v_lshlrev_b32_e32 v34, 8, v171
	s_add_i32 s4, s4, 0x14000
	v_and_b32_e32 v34, 0x1f00, v34
	v_add_u32_e32 v34, s4, v34
	v_bitop3_b32 v36, v193, v170, 15 bitop3:0x78
	v_and_b32_e32 v35, 15, v170
	v_pk_mul_f32 v[18:19], v[18:19], v[0:1] op_sel_hi:[1,0]
	v_pk_mul_f32 v[20:21], v[20:21], v[0:1] op_sel_hi:[1,0]
	v_lshl_add_u32 v36, v36, 4, v34
	ds_write_b128 v36, v[18:21]
	v_pk_mul_f32 v[18:19], v[22:23], v[0:1] op_sel_hi:[1,0]
	v_bitop3_b32 v22, v193, v35, 2 bitop3:0x36
	v_pk_mul_f32 v[20:21], v[24:25], v[0:1] op_sel_hi:[1,0]
	v_lshl_add_u32 v22, v22, 4, v34
	ds_write_b128 v22, v[18:21]
	v_bitop3_b32 v22, v193, v35, 4 bitop3:0x36
	v_pk_mul_f32 v[18:19], v[26:27], v[0:1] op_sel_hi:[1,0]
	v_pk_mul_f32 v[20:21], v[28:29], v[0:1] op_sel_hi:[1,0]
	v_lshl_add_u32 v22, v22, 4, v34
	ds_write_b128 v22, v[18:21]
	v_bitop3_b32 v22, v193, v35, 6 bitop3:0x36
	v_pk_mul_f32 v[18:19], v[30:31], v[0:1] op_sel_hi:[1,0]
	v_pk_mul_f32 v[20:21], v[32:33], v[0:1] op_sel_hi:[1,0]
	v_lshl_add_u32 v22, v22, 4, v34
	ds_write_b128 v22, v[18:21]
	v_bitop3_b32 v18, v193, v35, 8 bitop3:0x36
	v_pk_mul_f32 v[2:3], v[2:3], v[0:1] op_sel_hi:[1,0]
	v_pk_mul_f32 v[4:5], v[4:5], v[0:1] op_sel_hi:[1,0]
	v_lshl_add_u32 v18, v18, 4, v34
	ds_write_b128 v18, v[2:5]
	v_pk_mul_f32 v[2:3], v[6:7], v[0:1] op_sel_hi:[1,0]
	v_bitop3_b32 v6, v193, v35, 10 bitop3:0x36
	v_pk_mul_f32 v[4:5], v[8:9], v[0:1] op_sel_hi:[1,0]
	v_lshl_add_u32 v6, v6, 4, v34
	ds_write_b128 v6, v[2:5]
	v_bitop3_b32 v6, v193, v35, 12 bitop3:0x36
	v_pk_mul_f32 v[2:3], v[10:11], v[0:1] op_sel_hi:[1,0]
	v_pk_mul_f32 v[4:5], v[12:13], v[0:1] op_sel_hi:[1,0]
	v_lshl_add_u32 v6, v6, 4, v34
	ds_write_b128 v6, v[2:5]
	v_pk_mul_f32 v[2:3], v[14:15], v[0:1] op_sel_hi:[1,0]
	v_pk_mul_f32 v[4:5], v[16:17], v[0:1] op_sel_hi:[1,0]
	v_bitop3_b32 v0, v193, v35, 14 bitop3:0x36
	v_lshl_add_u32 v0, v0, 4, v34
	ds_write_b128 v0, v[2:5]
	v_and_b32_e32 v0, 7, v170
	v_lshrrev_b32_e32 v20, 3, v171
	v_lshlrev_b32_e32 v21, 1, v0
	v_bitop3_b32 v5, v21, v20, 1 bitop3:0x36
	v_lshlrev_b32_e32 v12, 16, v106
	v_lshlrev_b32_e32 v24, 4, v5
	v_and_b32_e32 v13, 0xffff0000, v106
	v_mul_f32_e32 v5, 0xbfb8aa3b, v12
	v_exp_f32_e32 v14, v5
	v_mul_f32_e32 v5, 0xbfb8aa3b, v13
	v_lshlrev_b32_e32 v0, 4, v0
	v_xor_b32_e32 v4, v20, v21
	v_exp_f32_e32 v15, v5
	v_lshl_add_u64 v[2:3], s[2:3], 0, v[0:1]
	v_lshl_add_u32 v0, v20, 8, s4
	v_lshlrev_b32_e32 v23, 4, v4
	v_add_u32_e32 v4, v0, v23
	v_add_u32_e32 v0, v0, v24
	ds_read_b128 v[4:7], v4
	ds_read_b128 v[8:11], v0
	v_add_f32_e32 v0, 1.0, v14
	v_lshlrev_b32_e32 v16, 16, v107
	v_rcp_f32_e32 v14, v0
	v_add_f32_e32 v0, 1.0, v15
	v_and_b32_e32 v17, 0xffff0000, v107
	v_mul_f32_e32 v15, 0xbfb8aa3b, v16
	v_exp_f32_e32 v18, v15
	v_mul_f32_e32 v15, 0xbfb8aa3b, v17
	v_exp_f32_e32 v19, v15
	v_rcp_f32_e32 v15, v0
	v_add_f32_e32 v0, 1.0, v18
	v_rcp_f32_e32 v18, v0
	v_add_f32_e32 v0, 1.0, v19
	v_rcp_f32_e32 v19, v0
	v_pk_mul_f32 v[12:13], v[14:15], v[12:13]
	v_and_b32_e32 v15, 0xffff0000, v109
	s_waitcnt lgkmcnt(1)
	v_pk_mul_f32 v[4:5], v[12:13], v[4:5]
	v_pk_mul_f32 v[12:13], v[18:19], v[16:17]
	v_cvt_pk_bf16_f32 v4, v4, v5
	v_pk_mul_f32 v[6:7], v[12:13], v[6:7]
	v_lshlrev_b32_e32 v12, 16, v108
	v_and_b32_e32 v13, 0xffff0000, v108
	v_mul_f32_e32 v0, 0xbfb8aa3b, v12
	v_exp_f32_e32 v0, v0
	v_mul_f32_e32 v5, 0xbfb8aa3b, v13
	v_exp_f32_e32 v14, v5
	v_cvt_pk_bf16_f32 v5, v6, v7
	v_add_f32_e32 v0, 1.0, v0
	v_rcp_f32_e32 v6, v0
	v_add_f32_e32 v0, 1.0, v14
	v_lshlrev_b32_e32 v14, 16, v109
	v_mul_f32_e32 v7, 0xbfb8aa3b, v14
	v_exp_f32_e32 v16, v7
	v_mul_f32_e32 v7, 0xbfb8aa3b, v15
	v_exp_f32_e32 v17, v7
	v_rcp_f32_e32 v7, v0
	v_add_f32_e32 v0, 1.0, v16
	v_rcp_f32_e32 v16, v0
	v_add_f32_e32 v0, 1.0, v17
	v_rcp_f32_e32 v17, v0
	v_pk_mul_f32 v[6:7], v[6:7], v[12:13]
	v_lshlrev_b32_e32 v0, 11, v20
	s_waitcnt lgkmcnt(0)
	v_pk_mul_f32 v[6:7], v[6:7], v[8:9]
	v_pk_mul_f32 v[8:9], v[16:17], v[14:15]
	v_or_b32_e32 v22, 1, v21
	v_pk_mul_f32 v[8:9], v[8:9], v[10:11]
	v_cvt_pk_bf16_f32 v6, v6, v7
	v_cvt_pk_bf16_f32 v7, v8, v9
	v_lshl_add_u64 v[8:9], v[2:3], 0, v[0:1]
	v_or_b32_e32 v0, 8, v20
	global_store_dwordx4 v[8:9], v[4:7], off
	v_lshlrev_b32_e32 v12, 16, v102
	v_and_b32_e32 v13, 0xffff0000, v102
	v_lshl_add_u32 v4, v0, 8, s4
	v_bitop3_b32 v5, v20, v21, 8 bitop3:0x36
	v_bitop3_b32 v6, v20, v22, 8 bitop3:0x36
	v_lshl_add_u32 v5, v5, 4, v4
	v_lshl_add_u32 v8, v6, 4, v4
	v_mul_f32_e32 v4, 0xbfb8aa3b, v12
	v_exp_f32_e32 v14, v4
	v_mul_f32_e32 v4, 0xbfb8aa3b, v13
	v_lshlrev_b32_e32 v16, 16, v103
	v_and_b32_e32 v17, 0xffff0000, v103
	v_exp_f32_e32 v15, v4
	v_mul_f32_e32 v18, 0xbfb8aa3b, v16
	v_mul_f32_e32 v19, 0xbfb8aa3b, v17
	v_exp_f32_e32 v18, v18
	v_exp_f32_e32 v19, v19
	v_add_f32_e32 v14, 1.0, v14
	v_add_f32_e32 v15, 1.0, v15
	v_rcp_f32_e32 v14, v14
	v_rcp_f32_e32 v15, v15
	v_add_f32_e32 v18, 1.0, v18
	v_add_f32_e32 v19, 1.0, v19
	ds_read_b128 v[4:7], v5
	ds_read_b128 v[8:11], v8
	v_rcp_f32_e32 v18, v18
	v_rcp_f32_e32 v19, v19
	v_pk_mul_f32 v[12:13], v[14:15], v[12:13]
	v_lshlrev_b32_e32 v0, 11, v0
	s_waitcnt lgkmcnt(1)
; DI float bf2f(unsigned h) { return __uint_as_float(h << 16); }
; DI unsigned cvtpk(float lo, float hi) { f32x2_t v = {lo, hi}; bf16x2_t b = __builtin_convertvector(v, bf16x2_t); return __builtin_bit_cast(unsigned, b); }
; DI float silu_f(float z) { return z * sigm_f(z); }
; DI void write_out_z(const f32x16& o0, const f32x16& o1, float sc, const u32x4 (&zpre)[4], bf16* orow0, size_t opitch, float* st, int lane) {
;     ...
;     for (int j = 0; j < 4; ++j) {
;         const int row = (lane >> 3) + 8 * j, c = lane & 7;
;         const f32x4 a = *(const f32x4*)(st + row * 64 + (((2 * c) ^ (row & 15)) << 2)), b = *(const f32x4*)(st + row * 64 + (((2 * c + 1) ^ (row & 15)) << 2));
;         const u32x4 zz = zpre[j];
;         u32x4 w;
;         w.x = cvtpk(a[0] * silu_f(bf2f(zz.x & 0xffffu)), a[1] * silu_f(bf2f(zz.x >> 16)));
;         w.y = cvtpk(a[2] * silu_f(bf2f(zz.y & 0xffffu)), a[3] * silu_f(bf2f(zz.y >> 16)));
;         w.z = cvtpk(b[0] * silu_f(bf2f(zz.z & 0xffffu)), b[1] * silu_f(bf2f(zz.z >> 16)));
;         w.w = cvtpk(b[2] * silu_f(bf2f(zz.w & 0xffffu)), b[3] * silu_f(bf2f(zz.w >> 16)));
;         *(u32x4*)(orow0 + (size_t)row * opitch + 8 * c) = w;
;     }
	v_pk_mul_f32 v[4:5], v[12:13], v[4:5]
	v_pk_mul_f32 v[12:13], v[18:19], v[16:17]
	v_cvt_pk_bf16_f32 v4, v4, v5
	v_pk_mul_f32 v[6:7], v[12:13], v[6:7]
	v_lshlrev_b32_e32 v12, 16, v104
	v_and_b32_e32 v13, 0xffff0000, v104
	v_mul_f32_e32 v5, 0xbfb8aa3b, v12
	v_exp_f32_e32 v14, v5
	v_mul_f32_e32 v5, 0xbfb8aa3b, v13
	v_exp_f32_e32 v15, v5
	v_cvt_pk_bf16_f32 v5, v6, v7
	v_add_f32_e32 v6, 1.0, v14
	v_lshlrev_b32_e32 v14, 16, v105
	v_add_f32_e32 v7, 1.0, v15
	v_and_b32_e32 v15, 0xffff0000, v105
	v_mul_f32_e32 v16, 0xbfb8aa3b, v14
	v_mul_f32_e32 v17, 0xbfb8aa3b, v15
	v_exp_f32_e32 v16, v16
	v_exp_f32_e32 v17, v17
	v_rcp_f32_e32 v6, v6
	v_rcp_f32_e32 v7, v7
	v_add_f32_e32 v16, 1.0, v16
	v_add_f32_e32 v17, 1.0, v17
	v_rcp_f32_e32 v16, v16
	v_rcp_f32_e32 v17, v17
	v_pk_mul_f32 v[6:7], v[6:7], v[12:13]
	v_lshlrev_b32_e32 v12, 16, v98
	s_waitcnt lgkmcnt(0)
	v_pk_mul_f32 v[6:7], v[6:7], v[8:9]
	v_pk_mul_f32 v[8:9], v[16:17], v[14:15]
	v_cvt_pk_bf16_f32 v6, v6, v7
	v_pk_mul_f32 v[8:9], v[8:9], v[10:11]
	v_and_b32_e32 v13, 0xffff0000, v98
	v_cvt_pk_bf16_f32 v7, v8, v9
	v_lshl_add_u64 v[8:9], v[2:3], 0, v[0:1]
	v_or_b32_e32 v0, 16, v20
	global_store_dwordx4 v[8:9], v[4:7], off
	v_lshlrev_b32_e32 v16, 16, v99
	v_and_b32_e32 v17, 0xffff0000, v99
	v_lshl_add_u32 v4, v0, 8, s4
	v_add_u32_e32 v5, v4, v23
	v_add_u32_e32 v8, v4, v24
	v_mul_f32_e32 v4, 0xbfb8aa3b, v12
	v_exp_f32_e32 v14, v4
	v_mul_f32_e32 v4, 0xbfb8aa3b, v13
	v_exp_f32_e32 v15, v4
	v_mul_f32_e32 v18, 0xbfb8aa3b, v16
	v_mul_f32_e32 v19, 0xbfb8aa3b, v17
	v_exp_f32_e32 v18, v18
	v_exp_f32_e32 v19, v19
	v_add_f32_e32 v14, 1.0, v14
	v_add_f32_e32 v15, 1.0, v15
	v_rcp_f32_e32 v14, v14
	v_rcp_f32_e32 v15, v15
	v_add_f32_e32 v18, 1.0, v18
	v_add_f32_e32 v19, 1.0, v19
	ds_read_b128 v[4:7], v5
	ds_read_b128 v[8:11], v8
	v_rcp_f32_e32 v18, v18
	v_rcp_f32_e32 v19, v19
	v_pk_mul_f32 v[12:13], v[14:15], v[12:13]
	v_lshlrev_b32_e32 v0, 11, v0
	s_waitcnt lgkmcnt(1)
	v_pk_mul_f32 v[4:5], v[12:13], v[4:5]
	v_pk_mul_f32 v[12:13], v[18:19], v[16:17]
	v_cvt_pk_bf16_f32 v4, v4, v5
	v_pk_mul_f32 v[6:7], v[12:13], v[6:7]
	v_lshlrev_b32_e32 v12, 16, v100
	v_and_b32_e32 v13, 0xffff0000, v100
	v_mul_f32_e32 v5, 0xbfb8aa3b, v12
	v_exp_f32_e32 v14, v5
	v_mul_f32_e32 v5, 0xbfb8aa3b, v13
	v_exp_f32_e32 v15, v5
	v_cvt_pk_bf16_f32 v5, v6, v7
	v_add_f32_e32 v6, 1.0, v14
	v_lshlrev_b32_e32 v14, 16, v101
	v_add_f32_e32 v7, 1.0, v15
	v_and_b32_e32 v15, 0xffff0000, v101
	v_mul_f32_e32 v16, 0xbfb8aa3b, v14
	v_mul_f32_e32 v17, 0xbfb8aa3b, v15
	v_exp_f32_e32 v16, v16
	v_exp_f32_e32 v17, v17
	v_rcp_f32_e32 v6, v6
	v_rcp_f32_e32 v7, v7
	v_add_f32_e32 v16, 1.0, v16
	v_add_f32_e32 v17, 1.0, v17
	v_rcp_f32_e32 v16, v16
	v_rcp_f32_e32 v17, v17
	v_pk_mul_f32 v[6:7], v[6:7], v[12:13]
	v_lshlrev_b32_e32 v12, 16, v86
	s_waitcnt lgkmcnt(0)
	v_pk_mul_f32 v[6:7], v[6:7], v[8:9]
	v_pk_mul_f32 v[8:9], v[16:17], v[14:15]
	v_cvt_pk_bf16_f32 v6, v6, v7
	v_pk_mul_f32 v[8:9], v[8:9], v[10:11]
	v_and_b32_e32 v13, 0xffff0000, v86
	v_cvt_pk_bf16_f32 v7, v8, v9
	v_lshl_add_u64 v[8:9], v[2:3], 0, v[0:1]
	v_or_b32_e32 v0, 24, v20
	global_store_dwordx4 v[8:9], v[4:7], off
	v_lshlrev_b32_e32 v16, 16, v87
	v_and_b32_e32 v17, 0xffff0000, v87
	v_lshl_add_u32 v4, v0, 8, s4
	v_bitop3_b32 v5, v0, v21, 15 bitop3:0x6c
	v_bitop3_b32 v6, v0, v22, 15 bitop3:0x6c
	v_lshl_add_u32 v5, v5, 4, v4
	v_lshl_add_u32 v8, v6, 4, v4
	v_mul_f32_e32 v4, 0xbfb8aa3b, v12
	v_exp_f32_e32 v14, v4
	v_mul_f32_e32 v4, 0xbfb8aa3b, v13
	v_exp_f32_e32 v15, v4
	v_mul_f32_e32 v18, 0xbfb8aa3b, v16
	v_mul_f32_e32 v19, 0xbfb8aa3b, v17
	v_exp_f32_e32 v18, v18
	v_exp_f32_e32 v19, v19
	v_add_f32_e32 v14, 1.0, v14
	v_add_f32_e32 v15, 1.0, v15
	v_rcp_f32_e32 v14, v14
	v_rcp_f32_e32 v15, v15
	v_add_f32_e32 v18, 1.0, v18
	v_add_f32_e32 v19, 1.0, v19
	ds_read_b128 v[4:7], v5
	ds_read_b128 v[8:11], v8
	v_rcp_f32_e32 v18, v18
	v_rcp_f32_e32 v19, v19
	v_pk_mul_f32 v[12:13], v[14:15], v[12:13]
	v_lshlrev_b32_e32 v0, 11, v0
	s_waitcnt lgkmcnt(1)
	v_pk_mul_f32 v[4:5], v[12:13], v[4:5]
	v_pk_mul_f32 v[12:13], v[18:19], v[16:17]
	v_cvt_pk_bf16_f32 v4, v4, v5
	v_pk_mul_f32 v[6:7], v[12:13], v[6:7]
	v_lshlrev_b32_e32 v12, 16, v88
	v_and_b32_e32 v13, 0xffff0000, v88
	v_mul_f32_e32 v5, 0xbfb8aa3b, v12
	v_exp_f32_e32 v14, v5
	v_mul_f32_e32 v5, 0xbfb8aa3b, v13
	v_exp_f32_e32 v15, v5
	v_cvt_pk_bf16_f32 v5, v6, v7
	v_add_f32_e32 v6, 1.0, v14
	v_lshlrev_b32_e32 v14, 16, v89
	v_add_f32_e32 v7, 1.0, v15
	v_and_b32_e32 v15, 0xffff0000, v89
	v_mul_f32_e32 v16, 0xbfb8aa3b, v14
	v_mul_f32_e32 v17, 0xbfb8aa3b, v15
	v_exp_f32_e32 v16, v16
	v_exp_f32_e32 v17, v17
	v_rcp_f32_e32 v6, v6
	v_rcp_f32_e32 v7, v7
	v_add_f32_e32 v16, 1.0, v16
	v_add_f32_e32 v17, 1.0, v17
	v_rcp_f32_e32 v16, v16
	v_rcp_f32_e32 v17, v17
	v_pk_mul_f32 v[6:7], v[6:7], v[12:13]
	v_lshl_add_u64 v[2:3], v[2:3], 0, v[0:1]
	s_waitcnt lgkmcnt(0)
; DI float bf2f(unsigned h) { return __uint_as_float(h << 16); }
; DI void fox_unit(const bf16* PR, const float* AUX, const float* bfp, bf16* MIX, char* sm, int b, int h, int qb, bool do_cs) {
;     ...
;     const int t = q0 + 32 * wid + r32;
;     bf16x8 qr[5];
; #pragma unroll
;     for (int d0 = 0; d0 < 4; ++d0) qr[d0] = *(const bf16x8*)(PR + (rb + t) * NP + C_FQ + 64 * h + 16 * d0 + 8 * hi);
;     { const short one = hi ? (short)0 : (short)0x3F80; qr[4] = (bf16x8){one, one, one, 0, 0, 0, 0, 0}; }
;     const float cref = cbuf[q0];
;     const bf16* Kb = PR + rb * NP + C_FK + 64 * h; const bf16* Vb = PR + rb * NP + C_FV + 64 * h;
;     float m = MINIT, l = 0.f; f32x16 o0, o1;
; #pragma unroll
;     for (int i = 0; i < 16; ++i) { o0[i] = 0.f; o1[i] = 0.f; }
;     unsigned z_ = 0u; asm volatile("" : "+v"(z_)); u32x4 kr, vr, ar = {z_, z_, z_, z_};
;     const int wq0 = q0 + 32 * wid;
;     u32x4 zpre[4];
;     const bf16* zrow0 = PR + (rb + wq0) * NP + C_FZ + 64 * h;
;     float q1 = 0.f;
; #pragma unroll
;     for (int d0 = 0; d0 < 4; ++d0)
; #pragma unroll
;         for (int j = 0; j < 8; ++j) q1 += fabsf(bf2f((unsigned)(unsigned short)qr[d0][j]));
;     q1 += __shfl_xor(q1, 32);
	v_pk_mul_f32 v[6:7], v[6:7], v[8:9]
	v_pk_mul_f32 v[8:9], v[16:17], v[14:15]
	v_cvt_pk_bf16_f32 v6, v6, v7
	v_pk_mul_f32 v[8:9], v[8:9], v[10:11]
	v_mov_b32_e32 v193, v172
	v_cvt_pk_bf16_f32 v7, v8, v9
	global_store_dwordx4 v[2:3], v[4:7], off
	s_lshl_b32 s3, s13, 2
	v_readfirstlane_b32 s2, v193
	s_ashr_i32 s18, s2, 6
	s_lshl_b32 s26, s18, 5
	v_and_b32_e32 v12, 31, v193
	s_add_i32 s19, s26, s13
	v_or_b32_e32 v2, s19, v12
	v_ashrrev_i32_e32 v3, 31, v2
	v_lshl_add_u64 v[2:3], s[14:15], 0, v[2:3]
	v_lshlrev_b64 v[2:3], 13, v[2:3]
	v_bfe_u32 v194, v193, 5, 1
	v_lshl_add_u64 v[2:3], s[86:87], 0, v[2:3]
	v_lshl_add_u64 v[2:3], v[2:3], 0, s[8:9]
	v_lshlrev_b32_e32 v0, 4, v194
	v_lshl_add_u64 v[2:3], v[2:3], 0, v[0:1]
	global_load_dwordx4 v[84:87], v[2:3], off
	global_load_dwordx4 v[88:91], v[2:3], off offset:32
	global_load_dwordx4 v[92:95], v[2:3], off offset:64
	global_load_dwordx4 v[96:99], v[2:3], off offset:96
	s_add_i32 s3, s3, 0
	v_mov_b32_e32 v0, s3
	ds_read_b32 v35, v0 offset:36864
	s_ashr_i32 s3, s19, 31
	s_add_u32 s6, s14, s19
	s_addc_u32 s7, s15, s3
	v_and_b32_e32 v195, 63, v193
	v_mov_b32_e32 v2, v1
	s_cmpk_lt_i32 s25, 0xfe81
	s_waitcnt vmcnt(3)
	v_lshlrev_b32_e32 v0, 16, v84
	v_and_b32_e32 v3, 0xffff0000, v84
	v_add_f32_e64 v0, |v0|, |v3|
	v_lshlrev_b32_e32 v3, 16, v85
	v_add_f32_e64 v0, |v3|, v0
	v_and_b32_e32 v3, 0xffff0000, v85
	v_add_f32_e64 v0, |v3|, v0
	v_lshlrev_b32_e32 v3, 16, v86
	v_add_f32_e64 v0, |v3|, v0
	v_and_b32_e32 v3, 0xffff0000, v86
	v_add_f32_e64 v0, |v3|, v0
	v_lshlrev_b32_e32 v3, 16, v87
	v_add_f32_e64 v0, |v3|, v0
	v_and_b32_e32 v3, 0xffff0000, v87
	v_add_f32_e64 v0, |v3|, v0
	s_waitcnt vmcnt(2)
	v_lshlrev_b32_e32 v3, 16, v88
	v_add_f32_e64 v0, |v3|, v0
	v_and_b32_e32 v3, 0xffff0000, v88
	v_add_f32_e64 v0, |v3|, v0
	v_lshlrev_b32_e32 v3, 16, v89
	v_add_f32_e64 v0, |v3|, v0
	v_and_b32_e32 v3, 0xffff0000, v89
	v_add_f32_e64 v0, |v3|, v0
	v_lshlrev_b32_e32 v3, 16, v90
	v_add_f32_e64 v0, |v3|, v0
	v_and_b32_e32 v3, 0xffff0000, v90
	v_add_f32_e64 v0, |v3|, v0
	v_lshlrev_b32_e32 v3, 16, v91
	v_add_f32_e64 v0, |v3|, v0
	v_and_b32_e32 v3, 0xffff0000, v91
	v_add_f32_e64 v0, |v3|, v0
	s_waitcnt vmcnt(1)
	v_lshlrev_b32_e32 v3, 16, v92
	v_add_f32_e64 v0, |v3|, v0
	v_and_b32_e32 v3, 0xffff0000, v92
	v_add_f32_e64 v0, |v3|, v0
	v_lshlrev_b32_e32 v3, 16, v93
	v_add_f32_e64 v0, |v3|, v0
	v_and_b32_e32 v3, 0xffff0000, v93
	v_add_f32_e64 v0, |v3|, v0
	v_lshlrev_b32_e32 v3, 16, v94
	v_add_f32_e64 v0, |v3|, v0
	v_and_b32_e32 v3, 0xffff0000, v94
	v_add_f32_e64 v0, |v3|, v0
	v_lshlrev_b32_e32 v3, 16, v95
	v_add_f32_e64 v0, |v3|, v0
	v_and_b32_e32 v3, 0xffff0000, v95
	v_add_f32_e64 v0, |v3|, v0
	s_waitcnt vmcnt(0)
	v_lshlrev_b32_e32 v3, 16, v96
	v_add_f32_e64 v0, |v3|, v0
	v_and_b32_e32 v3, 0xffff0000, v96
	v_add_f32_e64 v0, |v3|, v0
	v_lshlrev_b32_e32 v3, 16, v97
	v_add_f32_e64 v0, |v3|, v0
	v_and_b32_e32 v3, 0xffff0000, v97
	v_add_f32_e64 v0, |v3|, v0
	v_lshlrev_b32_e32 v3, 16, v98
	v_add_f32_e64 v0, |v3|, v0
	v_and_b32_e32 v3, 0xffff0000, v98
	v_add_f32_e64 v0, |v3|, v0
	v_lshlrev_b32_e32 v3, 16, v99
	v_add_f32_e64 v0, |v3|, v0
	v_and_b32_e32 v3, 0xffff0000, v99
	v_add_f32_e64 v13, |v3|, v0
	ds_bpermute_b32 v14, v187, v13
	s_cbranch_scc1 .LBB0_376
	s_lshl_b64 s[4:5], s[6:7], 13
	s_add_u32 s3, s86, s4
	s_addc_u32 s5, s87, s5
	s_add_u32 s4, s3, s8
	s_addc_u32 s5, s5, s9
	s_cmp_lt_u32 s2, 64
	v_lshlrev_b32_e32 v0, 9, v195
	v_lshlrev_b32_e32 v196, 4, v193
	s_cselect_b64 s[2:3], -1, 0
	s_cmpk_gt_i32 s25, 0xff40
	v_and_b32_e32 v3, 0x7000, v0
	v_and_b32_e32 v0, 0x70, v196
	s_cselect_b64 s[14:15], -1, 0
	v_lshl_add_u64 v[8:9], s[4:5], 0, v[0:1]
	s_mov_b64 s[4:5], -1
	s_and_b64 vcc, exec, s[14:15]
	v_lshlrev_b32_e32 v10, 1, v3
	s_cbranch_vccnz .LBB0_370
	v_mov_b32_e32 v11, v1
	v_lshl_add_u64 v[4:5], v[8:9], 0, v[10:11]
	v_add_co_u32_e32 v6, vcc, 0x10000, v4
	s_mov_b64 s[4:5], 0
	s_nop 0
	v_addc_co_u32_e32 v7, vcc, 0, v5, vcc
	global_load_dwordx4 v[80:83], v[4:5], off offset:2304
	global_load_dwordx4 v[76:79], v[6:7], off offset:2304
	v_add_co_u32_e32 v6, vcc, 0x20000, v4
	s_nop 1
	v_addc_co_u32_e32 v7, vcc, 0, v5, vcc
	v_add_co_u32_e32 v4, vcc, 0x30000, v4
	s_nop 1
	v_addc_co_u32_e32 v5, vcc, 0, v5, vcc
	global_load_dwordx4 v[72:75], v[6:7], off offset:2304
	global_load_dwordx4 v[68:71], v[4:5], off offset:2304

; DI void fox_unit(const bf16* PR, const float* AUX, const float* bfp, bf16* MIX, char* sm, int b, int h, int qb, bool do_cs) {
;     ...
;     for (int it_ = -1, nt_ = (4 * qb + 4); it_ < nt_; ++it_) {
;         const bool more_ = it_ + 1 < nt_;
;         if (!more_) {
; #pragma unroll
;             for (int j = 0; j < 4; ++j) zpre[j] = *(const u32x4*)(zrow0 + (size_t)((lane >> 3) + 8 * j) * NP + 8 * (lane & 7));
;         }
.LBB0_386:
	s_add_i32 s25, s26, 1
	s_cmp_lt_i32 s25, s12
	s_cselect_b64 s[14:15], -1, 0
	s_mov_b64 s[16:17], -1
	s_and_b64 vcc, exec, s[14:15]
	s_cbranch_vccnz .LBB0_388
	global_load_dwordx4 v[80:83], v[164:165], off
	global_load_dwordx4 v[76:79], v[166:167], off
	global_load_dwordx4 v[72:75], v[168:169], off
	global_load_dwordx4 v[68:71], v[170:171], off
	s_mov_b64 s[16:17], 0

; DI float bf2f(unsigned h) { return __uint_as_float(h << 16); }
; #define MFMA32(a, b, c) __builtin_amdgcn_mfma_f32_32x32x16_bf16((a), (b), (c), 0, 0, 0)
; DI void qk_tile(const char* kb, const bf16x8 (&qr)[5], int r32, int hi, f32x16& x0, f32x16& x1) {
;     bf16x8 kf[10];
; #pragma unroll
;     for (int d0 = 0; d0 < 4; ++d0) {
;         kf[2 * d0] = *(const bf16x8*)(kb + (2 * d0 + hi) * 1024 + r32 * 16);
;         kf[2 * d0 + 1] = *(const bf16x8*)(kb + (2 * d0 + hi) * 1024 + 512 + r32 * 16);
;     }
;     kf[8] = *(const bf16x8*)(kb + 8192 + r32 * 16);
;     kf[9] = *(const bf16x8*)(kb + 8192 + 512 + r32 * 16);
;     asm volatile("s_waitcnt lgkmcnt(0)" ::: "memory");
; #pragma unroll
;     for (int i = 0; i < 16; ++i) { x0[i] = 0.f; x1[i] = 0.f; }
; #pragma unroll
;     for (int d0 = 0; d0 < 5; ++d0) { x0 = MFMA32(kf[2 * d0], qr[d0], x0); x1 = MFMA32(kf[2 * d0 + 1], qr[d0], x1); }
; }
; DI void fox_unit(const bf16* PR, const float* AUX, const float* bfp, bf16* MIX, char* sm, int b, int h, int qb, bool do_cs) {
;     ...
;         if (it_ >= 0) { const int kt = nt_ - 1 - it_; const char* cb = sm + (it_ & 1) * STG; { if (64 * kt <= wq0 + 31) {
;               bool skip_ = false;
;               if (64 * kt + 63 + 384 < q0) {
;                   unsigned kb_ = 0u;
; #pragma unroll
;                   for (int w = 0; w < 8; ++w) { const unsigned v_ = kmx[(it_ & 1) * 8 + w]; kb_ = v_ > kb_ ? v_ : kb_; }
;                   const float ub = C2 * (q1 * bf2f(kb_) + 8.f * (cref - cbuf[64 * kt + 63]));
;                   skip_ = __all(ub - m < -151.f);
;               }
;               if (!skip_) {
;                   f32x16 x0, x1; qk_tile(cb, qr, r32, hi, x0, x1); bf16x8 vf[8]; v_load(cb + 9216, lane, hi, vf);
;                   if (64 * kt + 63 > wq0) mask_tile(x0, x1, 0, t - 64 * kt, hi);
.LBB0_391:
.LBB0_392:
	s_add_i32 s16, s23, 0xfffffe81
	s_cmp_gt_i32 s16, s21
	s_cbranch_scc1 .LBB0_401
	s_and_b32 s26, s26, 1
	s_add_i32 s16, s23, 64
	s_cmp_ge_i32 s16, s13
	s_cselect_b64 s[16:17], -1, 0
	s_and_b64 vcc, exec, s[16:17]
	s_cbranch_vccnz .LBB0_395
	s_lshl_b32 s16, s26, 5
	s_add_i32 s16, s16, 0
	s_add_i32 s16, s16, 0x13580
	v_mov_b32_e32 v0, s16
	ds_read_b128 v[36:39], v0
	ds_read_b128 v[40:43], v0 offset:16
	v_mov_b32_e32 v0, s22
	ds_read_b32 v0, v0 offset:508
	s_waitcnt lgkmcnt(0)
	v_max_u32_e32 v36, v37, v36
	v_max3_u32 v36, v39, v38, v36
	v_max3_u32 v36, v41, v40, v36
	v_max3_u32 v36, v43, v42, v36
	v_lshlrev_b32_e32 v149, 16, v36
	v_sub_f32_e32 v162, v35, v0
	v_pk_mul_f32 v[36:37], v[162:163], v[148:149]
	s_nop 0
	v_add_f32_e32 v0, v36, v37
	v_fma_f32 v0, v0, s92, -v237
	v_cmp_gt_f32_e32 vcc, s60, v0
	s_cmp_lg_u64 vcc, exec
	s_cselect_b64 s[16:17], -1, 0
.LBB0_395:
	s_andn2_b64 vcc, exec, s[16:17]
	s_cbranch_vccnz .LBB0_401
	s_mulk_i32 s26, 0x4800
	s_add_i32 s16, s26, 0
	v_add_u32_e32 v0, s16, v198
	v_add_u32_e32 v111, v0, v199
	ds_read_b128 v[36:39], v111
	s_waitcnt vmcnt(4)
	ds_read_b128 v[40:43], v111 offset:512
	ds_read_b128 v[116:119], v111 offset:2048
	ds_read_b128 v[120:123], v111 offset:2560
	s_add_i32 s17, s23, 0xfffffec0
	s_cmp_le_i32 s17, s19
	s_waitcnt lgkmcnt(3)
	v_mfma_f32_32x32x16_bf16 v[52:67], v[36:39], v[84:87], 0
	s_waitcnt lgkmcnt(2)
	v_mfma_f32_32x32x16_bf16 v[36:51], v[40:43], v[84:87], 0
	s_waitcnt lgkmcnt(1)
	v_mfma_f32_32x32x16_bf16 v[52:67], v[116:119], v[88:91], v[52:67]
	s_waitcnt lgkmcnt(0)
	v_mfma_f32_32x32x16_bf16 v[36:51], v[120:123], v[88:91], v[36:51]
	ds_read_b128 v[116:119], v111 offset:4096
	ds_read_b128 v[120:123], v111 offset:4608
	s_waitcnt lgkmcnt(1)
	v_mfma_f32_32x32x16_bf16 v[52:67], v[116:119], v[92:95], v[52:67]
	s_waitcnt lgkmcnt(0)
	v_mfma_f32_32x32x16_bf16 v[36:51], v[120:123], v[92:95], v[36:51]
	ds_read_b128 v[116:119], v111 offset:6144
	ds_read_b128 v[120:123], v111 offset:6656
	s_waitcnt lgkmcnt(1)
	v_mfma_f32_32x32x16_bf16 v[52:67], v[116:119], v[96:99], v[52:67]
	ds_read_b128 v[116:119], v0 offset:8192
	ds_read_b128 v[238:241], v0 offset:8704
	v_add3_u32 v0, s16, v200, v197
	v_add3_u32 v0, v0, v201, v203
	ds_read_b64_tr_b16 v[144:145], v0 offset:9216
	ds_read_b64_tr_b16 v[146:147], v0 offset:9728
	ds_read_b64_tr_b16 v[136:137], v0 offset:10240
	ds_read_b64_tr_b16 v[138:139], v0 offset:10752
	ds_read_b64_tr_b16 v[140:141], v0 offset:13312
	ds_read_b64_tr_b16 v[142:143], v0 offset:13824
	ds_read_b64_tr_b16 v[132:133], v0 offset:14336
	ds_read_b64_tr_b16 v[134:135], v0 offset:14848
	s_waitcnt lgkmcnt(10)
	v_mfma_f32_32x32x16_bf16 v[36:51], v[120:123], v[96:99], v[36:51]
	s_waitcnt lgkmcnt(9)
	v_mfma_f32_32x32x16_bf16 v[52:67], v[116:119], v[112:115], v[52:67]
	ds_read_b64_tr_b16 v[128:129], v0 offset:11264
	ds_read_b64_tr_b16 v[130:131], v0 offset:11776
	ds_read_b64_tr_b16 v[120:121], v0 offset:12288
	ds_read_b64_tr_b16 v[122:123], v0 offset:12800
	ds_read_b64_tr_b16 v[124:125], v0 offset:15360
	ds_read_b64_tr_b16 v[126:127], v0 offset:15872
	ds_read_b64_tr_b16 v[116:117], v0 offset:16384
	ds_read_b64_tr_b16 v[118:119], v0 offset:16896
	s_waitcnt lgkmcnt(14)
	v_mfma_f32_32x32x16_bf16 v[36:51], v[238:241], v[112:115], v[36:51]
	s_cbranch_scc1 .LBB0_398
	v_cmp_le_i32_e32 vcc, v205, v236
	s_nop 9
	v_cndmask_b32_e32 v36, v180, v36, vcc
	v_cmp_lt_i32_e32 vcc, v204, v236
	s_nop 1
	v_cndmask_b32_e32 v53, v180, v53, vcc
	v_cmp_le_i32_e32 vcc, v204, v236
	s_nop 1
	v_cndmask_b32_e32 v52, v180, v52, vcc
	v_cmp_le_i32_e32 vcc, v206, v236
	s_nop 1
	v_cndmask_b32_e32 v37, v180, v37, vcc
	v_cmp_le_i32_e32 vcc, v207, v236
	s_nop 1
	v_cndmask_b32_e32 v54, v180, v54, vcc
	v_cmp_le_i32_e32 vcc, v208, v236
	s_nop 1
	v_cndmask_b32_e32 v38, v180, v38, vcc
	v_cmp_le_i32_e32 vcc, v209, v236
	s_nop 1
	v_cndmask_b32_e32 v55, v180, v55, vcc
	v_cmp_le_i32_e32 vcc, v210, v236
	s_nop 1
	v_cndmask_b32_e32 v39, v180, v39, vcc
	v_cmp_le_i32_e32 vcc, v211, v236
	s_nop 1
	v_cndmask_b32_e32 v56, v180, v56, vcc
	v_cmp_le_i32_e32 vcc, v212, v236
	s_nop 1
	v_cndmask_b32_e32 v40, v180, v40, vcc
	v_cmp_le_i32_e32 vcc, v213, v236
	s_nop 1
	v_cndmask_b32_e32 v57, v180, v57, vcc
	v_cmp_le_i32_e32 vcc, v214, v236
	s_nop 1
	v_cndmask_b32_e32 v41, v180, v41, vcc
	v_cmp_le_i32_e32 vcc, v215, v236
	s_nop 1
	v_cndmask_b32_e32 v58, v180, v58, vcc
	v_cmp_le_i32_e32 vcc, v216, v236
	s_nop 1
	v_cndmask_b32_e32 v42, v180, v42, vcc
	v_cmp_le_i32_e32 vcc, v217, v236
	s_nop 1
	v_cndmask_b32_e32 v59, v180, v59, vcc
	v_cmp_le_i32_e32 vcc, v218, v236
	s_nop 1
	v_cndmask_b32_e32 v43, v180, v43, vcc
	v_cmp_le_i32_e32 vcc, v219, v236
	s_nop 1
	v_cndmask_b32_e32 v60, v180, v60, vcc
	v_cmp_le_i32_e32 vcc, v220, v236
	s_nop 1
	v_cndmask_b32_e32 v44, v180, v44, vcc
	v_cmp_le_i32_e32 vcc, v221, v236
	s_nop 1
	v_cndmask_b32_e32 v61, v180, v61, vcc
	v_cmp_le_i32_e32 vcc, v222, v236
	s_nop 1
	v_cndmask_b32_e32 v45, v180, v45, vcc
	v_cmp_le_i32_e32 vcc, v223, v236
	s_nop 1
	v_cndmask_b32_e32 v62, v180, v62, vcc
	v_cmp_le_i32_e32 vcc, v224, v236
	s_nop 1
	v_cndmask_b32_e32 v46, v180, v46, vcc
	v_cmp_le_i32_e32 vcc, v225, v236
	s_nop 1
	v_cndmask_b32_e32 v63, v180, v63, vcc
	v_cmp_le_i32_e32 vcc, v226, v236
	s_nop 1
	v_cndmask_b32_e32 v47, v180, v47, vcc
	v_cmp_le_i32_e32 vcc, v227, v236
	s_nop 1
	v_cndmask_b32_e32 v64, v180, v64, vcc
	v_cmp_le_i32_e32 vcc, v228, v236
	s_nop 1
	v_cndmask_b32_e32 v48, v180, v48, vcc
	v_cmp_le_i32_e32 vcc, v229, v236
	s_nop 1
	v_cndmask_b32_e32 v65, v180, v65, vcc
	v_cmp_le_i32_e32 vcc, v230, v236
	s_nop 1
	v_cndmask_b32_e32 v49, v180, v49, vcc
	v_cmp_le_i32_e32 vcc, v231, v236
	s_nop 1
	v_cndmask_b32_e32 v66, v180, v66, vcc
	v_cmp_le_i32_e32 vcc, v232, v236
	s_nop 1
	v_cndmask_b32_e32 v50, v180, v50, vcc
	v_cmp_le_i32_e32 vcc, v233, v236
	s_nop 1
	v_cndmask_b32_e32 v67, v180, v67, vcc
	v_cmp_le_i32_e32 vcc, v234, v236
	s_nop 1
	v_cndmask_b32_e32 v51, v180, v51, vcc

; DI float bf2f(unsigned h) { return __uint_as_float(h << 16); }
; DI unsigned cvtpk(float lo, float hi) { f32x2_t v = {lo, hi}; bf16x2_t b = __builtin_convertvector(v, bf16x2_t); return __builtin_bit_cast(unsigned, b); }
; DI float silu_f(float z) { return z * sigm_f(z); }
; DI void write_out_z(const f32x16& o0, const f32x16& o1, float sc, const u32x4 (&zpre)[4], bf16* orow0, size_t opitch, float* st, int lane) {
;     const int q = lane & 31, hi = lane >> 5;
; #pragma unroll
;     for (int d0 = 0; d0 < 2; ++d0)
; #pragma unroll
;         for (int gq = 0; gq < 4; ++gq) {
;             const int ch = 8 * d0 + 2 * gq + hi; const f32x16& o = d0 ? o1 : o0;
;             *(f32x4*)(st + q * 64 + ((ch ^ (q & 15)) << 2)) = (f32x4){o[4 * gq] * sc, o[4 * gq + 1] * sc, o[4 * gq + 2] * sc, o[4 * gq + 3] * sc};
;         }
; #pragma unroll
;     for (int j = 0; j < 4; ++j) {
;         const int row = (lane >> 3) + 8 * j, c = lane & 7;
;         const f32x4 a = *(const f32x4*)(st + row * 64 + (((2 * c) ^ (row & 15)) << 2)), b = *(const f32x4*)(st + row * 64 + (((2 * c + 1) ^ (row & 15)) << 2));
;         const u32x4 zz = zpre[j];
;         u32x4 w;
;         w.x = cvtpk(a[0] * silu_f(bf2f(zz.x & 0xffffu)), a[1] * silu_f(bf2f(zz.x >> 16)));
;         w.y = cvtpk(a[2] * silu_f(bf2f(zz.y & 0xffffu)), a[3] * silu_f(bf2f(zz.y >> 16)));
;         w.z = cvtpk(b[0] * silu_f(bf2f(zz.z & 0xffffu)), b[1] * silu_f(bf2f(zz.z >> 16)));
;         w.w = cvtpk(b[2] * silu_f(bf2f(zz.w & 0xffffu)), b[3] * silu_f(bf2f(zz.w >> 16)));
;         *(u32x4*)(orow0 + (size_t)row * opitch + 8 * c) = w;
;     }
; }
; DI void fox_unit(const bf16* PR, const float* AUX, const float* bfp, bf16* MIX, char* sm, int b, int h, int qb, bool do_cs) {
;     ...
;     const float lt = l + __shfl_xor(l, 32);
;     write_out_z(o0, o1, lt > 0.f ? 1.f / lt : 0.f, zpre, MIX + (rb + wq0) * D + 64 * h, D, (float*)(sm + L_TACC) + wid * 2048, lane);
.LBB0_412:
	s_waitcnt vmcnt(0)
	ds_bpermute_b32 v0, v187, v34
	s_lshl_b64 s[2:3], s[6:7], 11
	s_add_u32 s2, s96, s2
	s_addc_u32 s3, s97, s3
	s_add_u32 s2, s2, s8
	s_waitcnt lgkmcnt(0)
	v_add_f32_e32 v0, v34, v0
	v_div_scale_f32 v34, s[4:5], v0, v0, 1.0
	v_rcp_f32_e32 v35, v34
	v_div_scale_f32 v36, vcc, 1.0, v0, 1.0
	s_addc_u32 s3, s3, s9
	v_fma_f32 v37, -v34, v35, 1.0
	v_fmac_f32_e32 v35, v37, v35
	v_mul_f32_e32 v37, v36, v35
	v_fma_f32 v38, -v34, v37, v36
	v_fmac_f32_e32 v37, v38, v35
	v_fma_f32 v34, -v34, v37, v36
	v_div_fmas_f32 v34, v34, v35, v37
	v_div_fixup_f32 v34, v34, v0, 1.0
	v_cmp_lt_f32_e32 vcc, 0, v0
	s_lshl_b32 s4, s18, 13
	s_add_i32 s4, s4, 0
	v_cndmask_b32_e32 v0, 0, v34, vcc
	v_lshlrev_b32_e32 v34, 8, v195
	s_add_i32 s4, s4, 0x14000
	v_and_b32_e32 v34, 0x1f00, v34
	v_add_u32_e32 v34, s4, v34
	v_bitop3_b32 v36, v194, v193, 15 bitop3:0x78
	v_and_b32_e32 v35, 15, v193
	v_pk_mul_f32 v[18:19], v[18:19], v[0:1] op_sel_hi:[1,0]
	v_pk_mul_f32 v[20:21], v[20:21], v[0:1] op_sel_hi:[1,0]
	v_lshl_add_u32 v36, v36, 4, v34
	ds_write_b128 v36, v[18:21]
	v_pk_mul_f32 v[18:19], v[22:23], v[0:1] op_sel_hi:[1,0]
	v_bitop3_b32 v22, v194, v35, 2 bitop3:0x36
	v_pk_mul_f32 v[20:21], v[24:25], v[0:1] op_sel_hi:[1,0]
	v_lshl_add_u32 v22, v22, 4, v34
	ds_write_b128 v22, v[18:21]
	v_bitop3_b32 v22, v194, v35, 4 bitop3:0x36
	v_pk_mul_f32 v[18:19], v[26:27], v[0:1] op_sel_hi:[1,0]
	v_pk_mul_f32 v[20:21], v[28:29], v[0:1] op_sel_hi:[1,0]
	v_lshl_add_u32 v22, v22, 4, v34
	ds_write_b128 v22, v[18:21]
	v_bitop3_b32 v22, v194, v35, 6 bitop3:0x36
	v_pk_mul_f32 v[18:19], v[30:31], v[0:1] op_sel_hi:[1,0]
	v_pk_mul_f32 v[20:21], v[32:33], v[0:1] op_sel_hi:[1,0]
	v_lshl_add_u32 v22, v22, 4, v34
	ds_write_b128 v22, v[18:21]
	v_bitop3_b32 v18, v194, v35, 8 bitop3:0x36
	v_pk_mul_f32 v[2:3], v[2:3], v[0:1] op_sel_hi:[1,0]
	v_pk_mul_f32 v[4:5], v[4:5], v[0:1] op_sel_hi:[1,0]
	v_lshl_add_u32 v18, v18, 4, v34
	ds_write_b128 v18, v[2:5]
	v_pk_mul_f32 v[2:3], v[6:7], v[0:1] op_sel_hi:[1,0]
	v_bitop3_b32 v6, v194, v35, 10 bitop3:0x36
	v_pk_mul_f32 v[4:5], v[8:9], v[0:1] op_sel_hi:[1,0]
	v_lshl_add_u32 v6, v6, 4, v34
	ds_write_b128 v6, v[2:5]
	v_bitop3_b32 v6, v194, v35, 12 bitop3:0x36
	v_pk_mul_f32 v[2:3], v[10:11], v[0:1] op_sel_hi:[1,0]
	v_pk_mul_f32 v[4:5], v[12:13], v[0:1] op_sel_hi:[1,0]
	v_lshl_add_u32 v6, v6, 4, v34
	ds_write_b128 v6, v[2:5]
	v_pk_mul_f32 v[2:3], v[14:15], v[0:1] op_sel_hi:[1,0]
	v_pk_mul_f32 v[4:5], v[16:17], v[0:1] op_sel_hi:[1,0]
	v_bitop3_b32 v0, v194, v35, 14 bitop3:0x36
	v_lshl_add_u32 v0, v0, 4, v34
	ds_write_b128 v0, v[2:5]
	v_and_b32_e32 v0, 7, v193
	v_lshrrev_b32_e32 v20, 3, v195
	v_lshlrev_b32_e32 v21, 1, v0
	v_bitop3_b32 v5, v21, v20, 1 bitop3:0x36
	s_waitcnt vmcnt(3)
	v_lshlrev_b32_e32 v12, 16, v80
	v_lshlrev_b32_e32 v24, 4, v5
	v_and_b32_e32 v13, 0xffff0000, v80
	v_mul_f32_e32 v5, 0xbfb8aa3b, v12
	v_exp_f32_e32 v14, v5
	v_mul_f32_e32 v5, 0xbfb8aa3b, v13
	v_lshlrev_b32_e32 v0, 4, v0
	v_xor_b32_e32 v4, v20, v21
	v_exp_f32_e32 v15, v5
	v_lshl_add_u64 v[2:3], s[2:3], 0, v[0:1]
	v_lshl_add_u32 v0, v20, 8, s4
	v_lshlrev_b32_e32 v23, 4, v4
	v_add_u32_e32 v4, v0, v23
	v_add_u32_e32 v0, v0, v24
	ds_read_b128 v[4:7], v4
	ds_read_b128 v[8:11], v0
	v_add_f32_e32 v0, 1.0, v14
	v_lshlrev_b32_e32 v16, 16, v81
	v_rcp_f32_e32 v14, v0
	v_add_f32_e32 v0, 1.0, v15
	v_and_b32_e32 v17, 0xffff0000, v81
	v_mul_f32_e32 v15, 0xbfb8aa3b, v16
	v_exp_f32_e32 v18, v15
	v_mul_f32_e32 v15, 0xbfb8aa3b, v17
	v_exp_f32_e32 v19, v15
	v_rcp_f32_e32 v15, v0
	v_add_f32_e32 v0, 1.0, v18
	v_rcp_f32_e32 v18, v0
	v_add_f32_e32 v0, 1.0, v19
	v_rcp_f32_e32 v19, v0
	v_pk_mul_f32 v[12:13], v[14:15], v[12:13]
	v_and_b32_e32 v15, 0xffff0000, v83
	s_waitcnt lgkmcnt(1)
	v_pk_mul_f32 v[4:5], v[12:13], v[4:5]
	v_pk_mul_f32 v[12:13], v[18:19], v[16:17]
	v_cvt_pk_bf16_f32 v4, v4, v5
	v_pk_mul_f32 v[6:7], v[12:13], v[6:7]
	v_lshlrev_b32_e32 v12, 16, v82
	v_and_b32_e32 v13, 0xffff0000, v82
	v_mul_f32_e32 v0, 0xbfb8aa3b, v12
	v_exp_f32_e32 v0, v0
	v_mul_f32_e32 v5, 0xbfb8aa3b, v13
	v_exp_f32_e32 v14, v5
	v_cvt_pk_bf16_f32 v5, v6, v7
	v_add_f32_e32 v0, 1.0, v0
	v_rcp_f32_e32 v6, v0
	v_add_f32_e32 v0, 1.0, v14
	v_lshlrev_b32_e32 v14, 16, v83
	v_mul_f32_e32 v7, 0xbfb8aa3b, v14
	v_exp_f32_e32 v16, v7
	v_mul_f32_e32 v7, 0xbfb8aa3b, v15
	v_exp_f32_e32 v17, v7
	v_rcp_f32_e32 v7, v0
	v_add_f32_e32 v0, 1.0, v16
	v_rcp_f32_e32 v16, v0
	v_add_f32_e32 v0, 1.0, v17
	v_rcp_f32_e32 v17, v0
	v_pk_mul_f32 v[6:7], v[6:7], v[12:13]
	v_lshlrev_b32_e32 v0, 11, v20
	s_waitcnt lgkmcnt(0)
	v_pk_mul_f32 v[6:7], v[6:7], v[8:9]
	v_pk_mul_f32 v[8:9], v[16:17], v[14:15]
	v_or_b32_e32 v22, 1, v21
	v_pk_mul_f32 v[8:9], v[8:9], v[10:11]
	v_cvt_pk_bf16_f32 v6, v6, v7
	v_cvt_pk_bf16_f32 v7, v8, v9
	v_lshl_add_u64 v[8:9], v[2:3], 0, v[0:1]
	v_or_b32_e32 v0, 8, v20
	global_store_dwordx4 v[8:9], v[4:7], off
	s_waitcnt vmcnt(3)
	v_lshlrev_b32_e32 v12, 16, v76
	v_and_b32_e32 v13, 0xffff0000, v76
	v_lshl_add_u32 v4, v0, 8, s4
	v_bitop3_b32 v5, v20, v21, 8 bitop3:0x36
	v_bitop3_b32 v6, v20, v22, 8 bitop3:0x36
	v_lshl_add_u32 v5, v5, 4, v4
	v_lshl_add_u32 v8, v6, 4, v4
	v_mul_f32_e32 v4, 0xbfb8aa3b, v12
	v_exp_f32_e32 v14, v4
	v_mul_f32_e32 v4, 0xbfb8aa3b, v13
	v_lshlrev_b32_e32 v16, 16, v77
	v_and_b32_e32 v17, 0xffff0000, v77
	v_exp_f32_e32 v15, v4
	v_mul_f32_e32 v18, 0xbfb8aa3b, v16
	v_mul_f32_e32 v19, 0xbfb8aa3b, v17
	v_exp_f32_e32 v18, v18
	v_exp_f32_e32 v19, v19
	v_add_f32_e32 v14, 1.0, v14
	v_add_f32_e32 v15, 1.0, v15
	v_rcp_f32_e32 v14, v14
	v_rcp_f32_e32 v15, v15
	v_add_f32_e32 v18, 1.0, v18
	v_add_f32_e32 v19, 1.0, v19
	ds_read_b128 v[4:7], v5
	ds_read_b128 v[8:11], v8
	v_rcp_f32_e32 v18, v18
	v_rcp_f32_e32 v19, v19
	v_pk_mul_f32 v[12:13], v[14:15], v[12:13]
	v_lshlrev_b32_e32 v0, 11, v0
	s_waitcnt lgkmcnt(1)
; DI float bf2f(unsigned h) { return __uint_as_float(h << 16); }
; DI unsigned cvtpk(float lo, float hi) { f32x2_t v = {lo, hi}; bf16x2_t b = __builtin_convertvector(v, bf16x2_t); return __builtin_bit_cast(unsigned, b); }
; DI float silu_f(float z) { return z * sigm_f(z); }
; DI void write_out_z(const f32x16& o0, const f32x16& o1, float sc, const u32x4 (&zpre)[4], bf16* orow0, size_t opitch, float* st, int lane) {
;     ...
;     for (int j = 0; j < 4; ++j) {
;         const int row = (lane >> 3) + 8 * j, c = lane & 7;
;         const f32x4 a = *(const f32x4*)(st + row * 64 + (((2 * c) ^ (row & 15)) << 2)), b = *(const f32x4*)(st + row * 64 + (((2 * c + 1) ^ (row & 15)) << 2));
;         const u32x4 zz = zpre[j];
;         u32x4 w;
;         w.x = cvtpk(a[0] * silu_f(bf2f(zz.x & 0xffffu)), a[1] * silu_f(bf2f(zz.x >> 16)));
;         w.y = cvtpk(a[2] * silu_f(bf2f(zz.y & 0xffffu)), a[3] * silu_f(bf2f(zz.y >> 16)));
;         w.z = cvtpk(b[0] * silu_f(bf2f(zz.z & 0xffffu)), b[1] * silu_f(bf2f(zz.z >> 16)));
;         w.w = cvtpk(b[2] * silu_f(bf2f(zz.w & 0xffffu)), b[3] * silu_f(bf2f(zz.w >> 16)));
;         *(u32x4*)(orow0 + (size_t)row * opitch + 8 * c) = w;
;     }
	v_pk_mul_f32 v[4:5], v[12:13], v[4:5]
	v_pk_mul_f32 v[12:13], v[18:19], v[16:17]
	v_cvt_pk_bf16_f32 v4, v4, v5
	v_pk_mul_f32 v[6:7], v[12:13], v[6:7]
	v_lshlrev_b32_e32 v12, 16, v78
	v_and_b32_e32 v13, 0xffff0000, v78
	v_mul_f32_e32 v5, 0xbfb8aa3b, v12
	v_exp_f32_e32 v14, v5
	v_mul_f32_e32 v5, 0xbfb8aa3b, v13
	v_exp_f32_e32 v15, v5
	v_cvt_pk_bf16_f32 v5, v6, v7
	v_add_f32_e32 v6, 1.0, v14
	v_lshlrev_b32_e32 v14, 16, v79
	v_add_f32_e32 v7, 1.0, v15
	v_and_b32_e32 v15, 0xffff0000, v79
	v_mul_f32_e32 v16, 0xbfb8aa3b, v14
	v_mul_f32_e32 v17, 0xbfb8aa3b, v15
	v_exp_f32_e32 v16, v16
	v_exp_f32_e32 v17, v17
	v_rcp_f32_e32 v6, v6
	v_rcp_f32_e32 v7, v7
	v_add_f32_e32 v16, 1.0, v16
	v_add_f32_e32 v17, 1.0, v17
	v_rcp_f32_e32 v16, v16
	v_rcp_f32_e32 v17, v17
	v_pk_mul_f32 v[6:7], v[6:7], v[12:13]
	s_waitcnt vmcnt(2)
	v_lshlrev_b32_e32 v12, 16, v72
	s_waitcnt lgkmcnt(0)
	v_pk_mul_f32 v[6:7], v[6:7], v[8:9]
	v_pk_mul_f32 v[8:9], v[16:17], v[14:15]
	v_cvt_pk_bf16_f32 v6, v6, v7
	v_pk_mul_f32 v[8:9], v[8:9], v[10:11]
	v_and_b32_e32 v13, 0xffff0000, v72
	v_cvt_pk_bf16_f32 v7, v8, v9
	v_lshl_add_u64 v[8:9], v[2:3], 0, v[0:1]
	v_or_b32_e32 v0, 16, v20
	global_store_dwordx4 v[8:9], v[4:7], off
	v_lshlrev_b32_e32 v16, 16, v73
	v_and_b32_e32 v17, 0xffff0000, v73
	v_lshl_add_u32 v4, v0, 8, s4
	v_add_u32_e32 v5, v4, v23
	v_add_u32_e32 v8, v4, v24
	v_mul_f32_e32 v4, 0xbfb8aa3b, v12
	v_exp_f32_e32 v14, v4
	v_mul_f32_e32 v4, 0xbfb8aa3b, v13
	v_exp_f32_e32 v15, v4
	v_mul_f32_e32 v18, 0xbfb8aa3b, v16
	v_mul_f32_e32 v19, 0xbfb8aa3b, v17
	v_exp_f32_e32 v18, v18
	v_exp_f32_e32 v19, v19
	v_add_f32_e32 v14, 1.0, v14
	v_add_f32_e32 v15, 1.0, v15
	v_rcp_f32_e32 v14, v14
	v_rcp_f32_e32 v15, v15
	v_add_f32_e32 v18, 1.0, v18
	v_add_f32_e32 v19, 1.0, v19
	ds_read_b128 v[4:7], v5
	ds_read_b128 v[8:11], v8
	v_rcp_f32_e32 v18, v18
	v_rcp_f32_e32 v19, v19
	v_pk_mul_f32 v[12:13], v[14:15], v[12:13]
	v_lshlrev_b32_e32 v0, 11, v0
	s_waitcnt lgkmcnt(1)
	v_pk_mul_f32 v[4:5], v[12:13], v[4:5]
	v_pk_mul_f32 v[12:13], v[18:19], v[16:17]
	v_cvt_pk_bf16_f32 v4, v4, v5
	v_pk_mul_f32 v[6:7], v[12:13], v[6:7]
	v_lshlrev_b32_e32 v12, 16, v74
	v_and_b32_e32 v13, 0xffff0000, v74
	v_mul_f32_e32 v5, 0xbfb8aa3b, v12
	v_exp_f32_e32 v14, v5
	v_mul_f32_e32 v5, 0xbfb8aa3b, v13
	v_exp_f32_e32 v15, v5
	v_cvt_pk_bf16_f32 v5, v6, v7
	v_add_f32_e32 v6, 1.0, v14
	v_lshlrev_b32_e32 v14, 16, v75
	v_add_f32_e32 v7, 1.0, v15
	v_and_b32_e32 v15, 0xffff0000, v75
	v_mul_f32_e32 v16, 0xbfb8aa3b, v14
	v_mul_f32_e32 v17, 0xbfb8aa3b, v15
	v_exp_f32_e32 v16, v16
	v_exp_f32_e32 v17, v17
	v_rcp_f32_e32 v6, v6
	v_rcp_f32_e32 v7, v7
	v_add_f32_e32 v16, 1.0, v16
	v_add_f32_e32 v17, 1.0, v17
	v_rcp_f32_e32 v16, v16
	v_rcp_f32_e32 v17, v17
	v_pk_mul_f32 v[6:7], v[6:7], v[12:13]
	s_waitcnt vmcnt(2)
	v_lshlrev_b32_e32 v12, 16, v68
	s_waitcnt lgkmcnt(0)
	v_pk_mul_f32 v[6:7], v[6:7], v[8:9]
	v_pk_mul_f32 v[8:9], v[16:17], v[14:15]
	v_cvt_pk_bf16_f32 v6, v6, v7
	v_pk_mul_f32 v[8:9], v[8:9], v[10:11]
	v_and_b32_e32 v13, 0xffff0000, v68
	v_cvt_pk_bf16_f32 v7, v8, v9
	v_lshl_add_u64 v[8:9], v[2:3], 0, v[0:1]
	v_or_b32_e32 v0, 24, v20
	global_store_dwordx4 v[8:9], v[4:7], off
	v_lshlrev_b32_e32 v16, 16, v69
	v_and_b32_e32 v17, 0xffff0000, v69
	v_lshl_add_u32 v4, v0, 8, s4
	v_bitop3_b32 v5, v0, v21, 15 bitop3:0x6c
	v_bitop3_b32 v6, v0, v22, 15 bitop3:0x6c
	v_lshl_add_u32 v5, v5, 4, v4
	v_lshl_add_u32 v8, v6, 4, v4
	v_mul_f32_e32 v4, 0xbfb8aa3b, v12
	v_exp_f32_e32 v14, v4
	v_mul_f32_e32 v4, 0xbfb8aa3b, v13
	v_exp_f32_e32 v15, v4
	v_mul_f32_e32 v18, 0xbfb8aa3b, v16
	v_mul_f32_e32 v19, 0xbfb8aa3b, v17
	v_exp_f32_e32 v18, v18
	v_exp_f32_e32 v19, v19
	v_add_f32_e32 v14, 1.0, v14
	v_add_f32_e32 v15, 1.0, v15
	v_rcp_f32_e32 v14, v14
	v_rcp_f32_e32 v15, v15
	v_add_f32_e32 v18, 1.0, v18
	v_add_f32_e32 v19, 1.0, v19
	ds_read_b128 v[4:7], v5
	ds_read_b128 v[8:11], v8
	v_rcp_f32_e32 v18, v18
	v_rcp_f32_e32 v19, v19
	v_pk_mul_f32 v[12:13], v[14:15], v[12:13]
	v_lshlrev_b32_e32 v0, 11, v0
	s_waitcnt lgkmcnt(1)
	v_pk_mul_f32 v[4:5], v[12:13], v[4:5]
	v_pk_mul_f32 v[12:13], v[18:19], v[16:17]
	v_cvt_pk_bf16_f32 v4, v4, v5
	v_pk_mul_f32 v[6:7], v[12:13], v[6:7]
	v_lshlrev_b32_e32 v12, 16, v70
	v_and_b32_e32 v13, 0xffff0000, v70
	v_mul_f32_e32 v5, 0xbfb8aa3b, v12
	v_exp_f32_e32 v14, v5
	v_mul_f32_e32 v5, 0xbfb8aa3b, v13
	v_exp_f32_e32 v15, v5
	v_cvt_pk_bf16_f32 v5, v6, v7
	v_add_f32_e32 v6, 1.0, v14
	v_lshlrev_b32_e32 v14, 16, v71
	v_add_f32_e32 v7, 1.0, v15
	v_and_b32_e32 v15, 0xffff0000, v71
	v_mul_f32_e32 v16, 0xbfb8aa3b, v14
	v_mul_f32_e32 v17, 0xbfb8aa3b, v15
	v_exp_f32_e32 v16, v16
	v_exp_f32_e32 v17, v17
	v_rcp_f32_e32 v6, v6
	v_rcp_f32_e32 v7, v7
	v_add_f32_e32 v16, 1.0, v16
	v_add_f32_e32 v17, 1.0, v17
	v_rcp_f32_e32 v16, v16
	v_rcp_f32_e32 v17, v17
	v_pk_mul_f32 v[6:7], v[6:7], v[12:13]
	v_lshl_add_u64 v[2:3], v[2:3], 0, v[0:1]
	s_waitcnt lgkmcnt(0)
	v_pk_mul_f32 v[6:7], v[6:7], v[8:9]
	v_pk_mul_f32 v[8:9], v[16:17], v[14:15]
	v_cvt_pk_bf16_f32 v6, v6, v7
	v_pk_mul_f32 v[8:9], v[8:9], v[10:11]
	s_nop 0
	v_cvt_pk_bf16_f32 v7, v8, v9
	global_store_dwordx4 v[2:3], v[4:7], off
